# kernel start: all kernel-argument lines requested together (second and third scalar loads hoisted to the first instructions)
# speedup vs baseline: 1.0046x; 1.0007x over previous
_Z6mk_fwd4Args:
	s_load_dwordx8 s[76:83], s[0:1], 0x80
	s_load_dword s88, s[0:1], 0xa0
	s_load_dwordx16 s[56:71], s[0:1], 0x0
	s_load_dword s98, s[0:1], 0x40
	s_mov_b32 s86, s2
	s_add_u32 s2, s0, 0xa0
	s_addc_u32 s3, s1, 0
	v_readfirstlane_b32 s89, v0
	v_writelane_b32 v251, s2, 0
	v_cmp_gt_u32_e32 vcc, 32, v0
	s_nop 0
	v_writelane_b32 v251, s3, 1
	s_and_saveexec_b64 s[4:5], vcc
	v_lshl_add_u32 v1, v0, 2, 0
	v_add_u32_e32 v1, 0x20140, v1
	v_mov_b32_e32 v2, 0
	ds_write_b32 v1, v2
	s_or_b64 exec, exec, s[4:5]
	s_waitcnt lgkmcnt(0)
	s_barrier
	s_add_u32 s90, s80, 0x1000
	s_getreg_b32 s2, hwreg(HW_REG_XCC_ID, 0, 4)
	s_addc_u32 s91, s81, 0
	s_and_b32 s2, s2, 15
	v_cmp_eq_u32_e64 s[52:53], 0, v0
	v_writelane_b32 v251, s2, 2
	s_and_saveexec_b64 s[4:5], s[52:53]
	s_cbranch_execz .LBB0_5
	s_mov_b64 s[6:7], exec
	v_mbcnt_lo_u32_b32 v1, s6, 0
	v_mbcnt_hi_u32_b32 v1, s7, v1
	v_cmp_eq_u32_e32 vcc, 0, v1
	s_and_b64 s[2:3], exec, vcc
	s_mov_b64 exec, s[2:3]
	s_cbranch_execz .LBB0_5
	v_readlane_b32 s2, v251, 2
	s_lshl_b32 s2, s2, 8
	s_bcnt1_i32_b64 s3, s[6:7]
	v_mov_b32_e32 v1, s2
	v_mov_b32_e32 v2, s3
	global_atomic_add v1, v2, s[90:91] offset:1024
.LBB0_5:
	s_or_b64 exec, exec, s[4:5]
	s_lshr_b32 s87, s89, 6
	s_movk_i32 s8, 0x400
	s_movk_i32 s10, 0x200
	s_movk_i32 s72, 0x100
	s_cmp_lt_i32 s82, 1
	s_cselect_b64 s[2:3], -1, 0
	s_cmp_gt_i32 s83, 0
	s_cselect_b64 s[4:5], -1, 0
	v_writelane_b32 v251, s10, 3
	s_and_b64 s[6:7], s[2:3], s[4:5]
	v_and_b32_e32 v198, 63, v0
	v_writelane_b32 v251, s11, 4
	s_andn2_b64 vcc, exec, s[6:7]
	v_writelane_b32 v251, s8, 5
	s_nop 1
	v_writelane_b32 v251, s9, 6
	s_cbranch_vccnz .LBB0_131
	s_cmpk_gt_i32 s86, 0xff
	s_waitcnt lgkmcnt(0)
	s_barrier
	s_cbranch_scc1 .LBB0_131
	v_mbcnt_lo_u32_b32 v1, -1, 0
	v_mbcnt_hi_u32_b32 v2, -1, v1
	v_and_b32_e32 v1, 64, v2
	v_add_u32_e32 v3, 64, v1
	v_xor_b32_e32 v1, 1, v2
	v_cmp_lt_i32_e32 vcc, v1, v3
	v_xor_b32_e32 v4, 2, v2
	s_mov_b64 s[10:11], 0x1000
	v_cndmask_b32_e32 v1, v2, v1, vcc
	v_cmp_lt_i32_e32 vcc, v4, v3
	s_mul_i32 s2, s87, 0xf0
	s_add_i32 s3, 0, 0x1f000
	v_cndmask_b32_e32 v4, v2, v4, vcc
	v_lshlrev_b32_e32 v46, 2, v4
	v_xor_b32_e32 v4, 4, v2
	v_cmp_lt_i32_e32 vcc, v4, v3
	s_add_i32 s2, s3, s2
	s_add_u32 s8, s80, 0x1100000
	v_cndmask_b32_e32 v4, v2, v4, vcc
	v_lshlrev_b32_e32 v47, 2, v4
	v_xor_b32_e32 v4, 8, v2
	v_cmp_lt_i32_e32 vcc, v4, v3
	v_lshlrev_b32_e32 v1, 2, v1
	v_cmp_gt_u32_e64 s[4:5], 60, v0
	v_cndmask_b32_e32 v4, v2, v4, vcc
	v_lshlrev_b32_e32 v48, 2, v4
	v_xor_b32_e32 v4, 16, v2
	v_cmp_lt_i32_e32 vcc, v4, v3
	s_addc_u32 s9, s81, 0
	v_mul_hi_u32_u24_e32 v27, 0x3000, v0
	v_cndmask_b32_e32 v4, v2, v4, vcc
	v_lshlrev_b32_e32 v49, 2, v4
	v_xor_b32_e32 v4, 32, v2
	v_cmp_lt_i32_e32 vcc, v4, v3
	v_mul_u32_u24_e32 v3, 0x1556, v0
	v_mul_u32_u24_e32 v26, 0x3000, v0
	v_cndmask_b32_e32 v2, v2, v4, vcc
	v_lshrrev_b32_e32 v4, 16, v3
	v_mul_lo_u16_e32 v3, 12, v4
	v_sub_u16_e32 v52, v0, v3
	v_or_b32_e32 v3, 0x200, v0
	v_lshlrev_b32_e32 v50, 2, v2
	v_lshlrev_b32_e32 v2, 2, v0
	v_mul_hi_u32_u24_e32 v29, 0x3000, v3
	v_mul_u32_u24_e32 v28, 0x3000, v3
	v_mov_b32_e32 v3, 0
	v_lshl_add_u64 v[30:31], s[58:59], 0, v[2:3]
	v_lshl_add_u64 v[32:33], v[30:31], 0, s[10:11]
	s_mov_b64 s[10:11], 0x2000
	v_lshl_add_u64 v[34:35], v[30:31], 0, s[10:11]
	s_mov_b64 s[10:11], 0x3000
	v_lshl_add_u64 v[36:37], v[30:31], 0, s[10:11]
	s_mov_b64 s[10:11], 0x1800
	v_lshl_add_u64 v[40:41], v[30:31], 0, s[10:11]
	s_mov_b64 s[10:11], 0x2800
	v_add_u32_e32 v51, s3, v2
	v_lshl_add_u64 v[42:43], v[30:31], 0, s[10:11]
	s_mov_b64 s[10:11], 0x3800
	s_movk_i32 s3, 0xc00
	v_cmp_eq_u32_e32 vcc, 0, v198
	v_lshl_add_u64 v[38:39], s[62:63], 0, v[2:3]
	v_lshl_add_u64 v[44:45], v[30:31], 0, s[10:11]
	v_mad_u32_u24 v53, v4, s3, v52
	s_mul_i32 s10, s86, 12
	s_mul_i32 s3, s88, 12
	s_mov_b32 s14, s86
	s_branch .LBB0_9
